# plus: static s_setprio 1 for waves 0-3 during the attention phase
# speedup vs baseline: 1.0069x; 1.0069x over previous
; DI void phase_attn1(const Params& p, char* smem) {
;   const int G = gridDim.x;
;   for (int round = 0; round * G < 512; ++round) {
;     const int j = (round & 1) ? (G - 1 - (int)blockIdx.x) : (int)blockIdx.x;
;     const int t = round * G + j;
;     if (t >= 512) continue;
;     const int qt = 15 - (t >> 5), bh = t & 31;
;     mla_item(p, bh >> 3, bh & 7, qt, smem);
;   }
.Lstag_10:
	s_waitcnt lgkmcnt(0)
	s_barrier
	v_readfirstlane_b32 s98, v206
	s_nop 0
	s_lshr_b32 s98, s98, 8
	s_cmp_eq_u32 s98, 0
	s_cbranch_scc0 .Lattn_prio_skip
	s_setprio 1
